# out-proj epilogue rewritten: accumulator tile transposed through LDS to row-major so residual loads/stores and bf16 xg stores are fully coalesced (256B/128B rows), rolling 3-slot prefetch of residual
# speedup vs baseline: 1.1298x; 1.0622x over previous
.LBB0_549:
	s_or_b64 exec, exec, s[4:5]
	v_mbcnt_lo_u32_b32 v200, -1, 0
	v_mbcnt_hi_u32_b32 v200, -1, v200
	v_and_b32_e32 v201, 15, v200
	v_lshrrev_b32_e32 v202, 4, v200
	s_lshr_b32 s36, s3, 6
	s_lshr_b32 s37, s36, 2
	s_and_b32 s38, s36, 3
	s_mul_i32 s39, s36, 0x1100
	v_mul_u32_u24_e32 v198, 0x110, v201
	v_lshl_add_u32 v198, v202, 4, v198
	v_add_u32_e32 v198, s39, v198
	v_mul_u32_u24_e32 v242, 0x110, v202
	v_lshl_add_u32 v242, v201, 4, v242
	v_add_u32_e32 v242, s39, v242
	s_lshl_b32 s40, s38, 7
	v_lshl_add_u32 v203, v201, 2, s40
	v_add_u32_e32 v203, 0x20400, v203
	ds_read_b32 v176, v203
	ds_read_b32 v178, v203 offset:64
	ds_read_b32 v180, v203 offset:512
	ds_read_b32 v182, v203 offset:576
	s_lshl_b32 s41, s37, 9
	v_lshl_add_u32 v243, v201, 5, s41
	v_add_u32_e32 v243, 0x20800, v243
	ds_read_b128 v[184:187], v243
	ds_read_b128 v[188:191], v243 offset:16
	s_lshl_b32 s40, s38, 17
	s_lshl_b32 s41, s37, 8
	s_add_i32 s40, s40, s41
	v_lshlrev_b32_e32 v232, 12, v202
	v_lshl_add_u32 v232, v201, 4, v232
	v_add_u32_e32 v232, s40, v232
	v_add_u32_e32 v233, 0x4000, v232
	v_add_u32_e32 v234, 0x8000, v232
	v_add_u32_e32 v235, 0xc000, v232
	v_lshrrev_b32_e32 v236, 1, v232
	v_lshrrev_b32_e32 v237, 1, v233
	v_lshrrev_b32_e32 v238, 1, v234
	v_lshrrev_b32_e32 v239, 1, v235
	s_lshl_b32 s40, s38, 10
	s_lshl_b32 s41, s37, 2
	s_add_i32 s40, s40, s41
	v_lshl_add_u32 v244, v202, 5, s40
	s_mov_b32 s46, s96
	s_cmp_lg_u32 s86, 0
	s_cbranch_scc1 .Loe_x_ws
	v_readlane_b32 s44, v254, 16
	v_readlane_b32 s45, v254, 17
	s_cmpk_lt_u32 s96, 0x1000
	s_cbranch_scc1 .Loe_x_done
	v_readlane_b32 s44, v254, 18
	v_readlane_b32 s45, v254, 19
	s_add_i32 s46, s96, 0xfffff000
	s_branch .Loe_x_done
.Loe_x_ws:
	s_mov_b64 s[44:45], s[8:9]
.Loe_x_done:
	s_lshl_b32 s47, s46, 12
	s_lshl_b32 s100, s94, 2
	s_add_u32 s47, s47, s100
	s_add_u32 s44, s44, s47
	s_addc_u32 s45, s45, 0
	s_lshl_b32 s47, s96, 12
	s_add_u32 s47, s47, s100
	s_add_u32 s48, s8, s47
	s_addc_u32 s49, s9, 0
	s_lshr_b32 s47, s47, 1
	s_add_u32 s50, s6, s47
	s_addc_u32 s51, s7, 0
	s_lshl_b32 s47, s96, 5
	s_lshl_b32 s100, s23, 3
	s_add_u32 s47, s47, s100
	s_add_u32 s42, s87, s47
	s_addc_u32 s43, s19, 0
	v_mov_b32_e32 v216, 0
	v_mov_b32_e32 v217, 0
	v_mov_b32_e32 v218, 0
	v_mov_b32_e32 v219, 0
	v_mov_b32_e32 v220, 0
	v_mov_b32_e32 v221, 0
	v_mov_b32_e32 v222, 0
	v_mov_b32_e32 v223, 0
	v_mov_b32_e32 v224, 0
	v_mov_b32_e32 v225, 0
	v_mov_b32_e32 v226, 0
	v_mov_b32_e32 v227, 0
	v_mov_b32_e32 v228, 0
	v_mov_b32_e32 v229, 0
	v_mov_b32_e32 v230, 0
	v_mov_b32_e32 v231, 0
	s_add_u32 s36, s44, 0x0
	s_addc_u32 s37, s45, 0
	global_load_dwordx4 v[128:131], v232, s[36:37]
	global_load_dwordx4 v[132:135], v233, s[36:37]
	global_load_dwordx4 v[136:139], v234, s[36:37]
	global_load_dwordx4 v[140:143], v235, s[36:37]
	s_add_u32 s36, s44, 0x10000
	s_addc_u32 s37, s45, 0
	global_load_dwordx4 v[144:147], v232, s[36:37]
	global_load_dwordx4 v[148:151], v233, s[36:37]
	global_load_dwordx4 v[152:155], v234, s[36:37]
	global_load_dwordx4 v[156:159], v235, s[36:37]
	s_add_u32 s36, s44, 0x80000
	s_addc_u32 s37, s45, 0
	global_load_dwordx4 v[160:163], v232, s[36:37]
	global_load_dwordx4 v[164:167], v233, s[36:37]
	global_load_dwordx4 v[168:171], v234, s[36:37]
	global_load_dwordx4 v[172:175], v235, s[36:37]
	s_waitcnt lgkmcnt(0)
	v_mov_b32_e32 v192, v184
	v_mov_b32_e32 v193, v186
	v_mov_b32_e32 v194, v188
	v_mov_b32_e32 v195, v190
	v_mov_b32_e32 v184, v185
	v_mov_b32_e32 v185, v187
	v_mov_b32_e32 v186, v189
	v_mov_b32_e32 v187, v191
	v_pk_mul_f32 v[48:49], v[48:49], v[176:177] op_sel_hi:[1,0]
	v_pk_mul_f32 v[50:51], v[50:51], v[176:177] op_sel_hi:[1,0]
	v_pk_mul_f32 v[116:117], v[116:117], v[176:177] op_sel_hi:[1,0]
	v_pk_mul_f32 v[118:119], v[118:119], v[176:177] op_sel_hi:[1,0]
	v_pk_mul_f32 v[124:125], v[124:125], v[176:177] op_sel_hi:[1,0]
	v_pk_mul_f32 v[126:127], v[126:127], v[176:177] op_sel_hi:[1,0]
	v_pk_mul_f32 v[108:109], v[108:109], v[176:177] op_sel_hi:[1,0]
	v_pk_mul_f32 v[110:111], v[110:111], v[176:177] op_sel_hi:[1,0]
	ds_write_b128 v198, v[48:51]
	ds_write_b128 v198, v[116:119] offset:64
	ds_write_b128 v198, v[124:127] offset:128
	ds_write_b128 v198, v[108:111] offset:192
	ds_read_b128 v[200:203], v242
	ds_read_b128 v[204:207], v242 offset:1088
	ds_read_b128 v[208:211], v242 offset:2176
	ds_read_b128 v[212:215], v242 offset:3264
	v_pk_mul_f32 v[60:61], v[60:61], v[178:179] op_sel_hi:[1,0]
	v_pk_mul_f32 v[62:63], v[62:63], v[178:179] op_sel_hi:[1,0]
	v_pk_mul_f32 v[88:89], v[88:89], v[178:179] op_sel_hi:[1,0]
	v_pk_mul_f32 v[90:91], v[90:91], v[178:179] op_sel_hi:[1,0]
	v_pk_mul_f32 v[120:121], v[120:121], v[178:179] op_sel_hi:[1,0]
	v_pk_mul_f32 v[122:123], v[122:123], v[178:179] op_sel_hi:[1,0]
	v_pk_mul_f32 v[100:101], v[100:101], v[178:179] op_sel_hi:[1,0]
	v_pk_mul_f32 v[102:103], v[102:103], v[178:179] op_sel_hi:[1,0]
	ds_write_b128 v198, v[60:63]
	ds_write_b128 v198, v[88:91] offset:64
	ds_write_b128 v198, v[120:123] offset:128
	ds_write_b128 v198, v[100:103] offset:192
	s_waitcnt lgkmcnt(4)
	s_waitcnt vmcnt(8)
	v_pk_fma_f32 v[128:129], v[200:201], v[192:193], v[128:129]
	v_pk_fma_f32 v[130:131], v[202:203], v[194:195], v[130:131]
	v_pk_fma_f32 v[132:133], v[204:205], v[192:193], v[132:133]
	v_pk_fma_f32 v[134:135], v[206:207], v[194:195], v[134:135]
	v_pk_fma_f32 v[136:137], v[208:209], v[192:193], v[136:137]
	v_pk_fma_f32 v[138:139], v[210:211], v[194:195], v[138:139]
	v_pk_fma_f32 v[140:141], v[212:213], v[192:193], v[140:141]
	v_pk_fma_f32 v[142:143], v[214:215], v[194:195], v[142:143]
	s_add_u32 s38, s48, 0x0
	s_addc_u32 s39, s49, 0
	v_fma_f32 v216, v128, v128, v216
	v_fma_f32 v216, v129, v129, v216
	v_fma_f32 v216, v130, v130, v216
	v_fma_f32 v216, v131, v131, v216
	global_store_dwordx4 v232, v[128:131], s[38:39]
	v_fma_f32 v217, v132, v132, v217
	v_fma_f32 v217, v133, v133, v217
	v_fma_f32 v217, v134, v134, v217
	v_fma_f32 v217, v135, v135, v217
	global_store_dwordx4 v233, v[132:135], s[38:39]
	v_fma_f32 v218, v136, v136, v218
	v_fma_f32 v218, v137, v137, v218
	v_fma_f32 v218, v138, v138, v218
	v_fma_f32 v218, v139, v139, v218
	global_store_dwordx4 v234, v[136:139], s[38:39]
	v_fma_f32 v219, v140, v140, v219
	v_fma_f32 v219, v141, v141, v219
	v_fma_f32 v219, v142, v142, v219
	v_fma_f32 v219, v143, v143, v219
	global_store_dwordx4 v235, v[140:143], s[38:39]
	s_cmp_eq_u32 s86, 3
	s_cbranch_scc1 .Loe_nxg0
	s_add_u32 s40, s50, 0x0
	s_addc_u32 s41, s51, 0
	v_pk_mul_f32 v[200:201], v[128:129], v[184:185]
	v_pk_mul_f32 v[202:203], v[130:131], v[186:187]
	v_pk_mul_f32 v[204:205], v[132:133], v[184:185]
	v_pk_mul_f32 v[206:207], v[134:135], v[186:187]
	v_pk_mul_f32 v[208:209], v[136:137], v[184:185]
	v_pk_mul_f32 v[210:211], v[138:139], v[186:187]
	v_pk_mul_f32 v[212:213], v[140:141], v[184:185]
	v_pk_mul_f32 v[214:215], v[142:143], v[186:187]
	v_cvt_pk_bf16_f32 v200, v200, v201
	v_cvt_pk_bf16_f32 v201, v202, v203
	v_cvt_pk_bf16_f32 v204, v204, v205
	v_cvt_pk_bf16_f32 v205, v206, v207
	v_cvt_pk_bf16_f32 v208, v208, v209
	v_cvt_pk_bf16_f32 v209, v210, v211
	v_cvt_pk_bf16_f32 v212, v212, v213
	v_cvt_pk_bf16_f32 v213, v214, v215
	global_store_dwordx2 v236, v[200:201], s[40:41]
	global_store_dwordx2 v237, v[204:205], s[40:41]
	global_store_dwordx2 v238, v[208:209], s[40:41]
	global_store_dwordx2 v239, v[212:213], s[40:41]
.Loe_nxg0:
	s_nop 1
	s_add_u32 s36, s44, 0x90000
	s_addc_u32 s37, s45, 0
	global_load_dwordx4 v[128:131], v232, s[36:37]
	global_load_dwordx4 v[132:135], v233, s[36:37]
	global_load_dwordx4 v[136:139], v234, s[36:37]
	global_load_dwordx4 v[140:143], v235, s[36:37]
	ds_read_b128 v[200:203], v242
	ds_read_b128 v[204:207], v242 offset:1088
	ds_read_b128 v[208:211], v242 offset:2176
	ds_read_b128 v[212:215], v242 offset:3264
	v_pk_mul_f32 v[52:53], v[52:53], v[180:181] op_sel_hi:[1,0]
	v_pk_mul_f32 v[54:55], v[54:55], v[180:181] op_sel_hi:[1,0]
	v_pk_mul_f32 v[84:85], v[84:85], v[180:181] op_sel_hi:[1,0]
	v_pk_mul_f32 v[86:87], v[86:87], v[180:181] op_sel_hi:[1,0]
	v_pk_mul_f32 v[112:113], v[112:113], v[180:181] op_sel_hi:[1,0]
	v_pk_mul_f32 v[114:115], v[114:115], v[180:181] op_sel_hi:[1,0]
	v_pk_mul_f32 v[96:97], v[96:97], v[180:181] op_sel_hi:[1,0]
	v_pk_mul_f32 v[98:99], v[98:99], v[180:181] op_sel_hi:[1,0]
	ds_write_b128 v198, v[52:55]
	ds_write_b128 v198, v[84:87] offset:64
	ds_write_b128 v198, v[112:115] offset:128
	ds_write_b128 v198, v[96:99] offset:192
	s_waitcnt lgkmcnt(4)
	s_waitcnt vmcnt(12)
	v_pk_fma_f32 v[144:145], v[200:201], v[192:193], v[144:145]
	v_pk_fma_f32 v[146:147], v[202:203], v[194:195], v[146:147]
	v_pk_fma_f32 v[148:149], v[204:205], v[192:193], v[148:149]
	v_pk_fma_f32 v[150:151], v[206:207], v[194:195], v[150:151]
	v_pk_fma_f32 v[152:153], v[208:209], v[192:193], v[152:153]
	v_pk_fma_f32 v[154:155], v[210:211], v[194:195], v[154:155]
	v_pk_fma_f32 v[156:157], v[212:213], v[192:193], v[156:157]
	v_pk_fma_f32 v[158:159], v[214:215], v[194:195], v[158:159]
	s_add_u32 s38, s48, 0x10000
	s_addc_u32 s39, s49, 0
	v_fma_f32 v220, v144, v144, v220
	v_fma_f32 v220, v145, v145, v220
	v_fma_f32 v220, v146, v146, v220
	v_fma_f32 v220, v147, v147, v220
	global_store_dwordx4 v232, v[144:147], s[38:39]
	v_fma_f32 v221, v148, v148, v221
	v_fma_f32 v221, v149, v149, v221
	v_fma_f32 v221, v150, v150, v221
	v_fma_f32 v221, v151, v151, v221
	global_store_dwordx4 v233, v[148:151], s[38:39]
	v_fma_f32 v222, v152, v152, v222
	v_fma_f32 v222, v153, v153, v222
	v_fma_f32 v222, v154, v154, v222
	v_fma_f32 v222, v155, v155, v222
	global_store_dwordx4 v234, v[152:155], s[38:39]
	v_fma_f32 v223, v156, v156, v223
	v_fma_f32 v223, v157, v157, v223
	v_fma_f32 v223, v158, v158, v223
	v_fma_f32 v223, v159, v159, v223
	global_store_dwordx4 v235, v[156:159], s[38:39]
	s_cmp_eq_u32 s86, 3
	s_cbranch_scc1 .Loe_nxg1
	s_add_u32 s40, s50, 0x8000
	s_addc_u32 s41, s51, 0
	v_pk_mul_f32 v[200:201], v[144:145], v[184:185]
	v_pk_mul_f32 v[202:203], v[146:147], v[186:187]
	v_pk_mul_f32 v[204:205], v[148:149], v[184:185]
	v_pk_mul_f32 v[206:207], v[150:151], v[186:187]
	v_pk_mul_f32 v[208:209], v[152:153], v[184:185]
	v_pk_mul_f32 v[210:211], v[154:155], v[186:187]
	v_pk_mul_f32 v[212:213], v[156:157], v[184:185]
	v_pk_mul_f32 v[214:215], v[158:159], v[186:187]
	v_cvt_pk_bf16_f32 v200, v200, v201
	v_cvt_pk_bf16_f32 v201, v202, v203
	v_cvt_pk_bf16_f32 v204, v204, v205
	v_cvt_pk_bf16_f32 v205, v206, v207
	v_cvt_pk_bf16_f32 v208, v208, v209
	v_cvt_pk_bf16_f32 v209, v210, v211
	v_cvt_pk_bf16_f32 v212, v212, v213
	v_cvt_pk_bf16_f32 v213, v214, v215
	global_store_dwordx2 v236, v[200:201], s[40:41]
	global_store_dwordx2 v237, v[204:205], s[40:41]
	global_store_dwordx2 v238, v[208:209], s[40:41]
	global_store_dwordx2 v239, v[212:213], s[40:41]
.Loe_nxg1:
	s_nop 1
	s_add_u32 s36, s44, 0x200
	s_addc_u32 s37, s45, 0
	global_load_dwordx4 v[144:147], v232, s[36:37]
	global_load_dwordx4 v[148:151], v233, s[36:37]
	global_load_dwordx4 v[152:155], v234, s[36:37]
	global_load_dwordx4 v[156:159], v235, s[36:37]
	ds_read_b128 v[200:203], v242
	ds_read_b128 v[204:207], v242 offset:1088
	ds_read_b128 v[208:211], v242 offset:2176
	ds_read_b128 v[212:215], v242 offset:3264
	v_pk_mul_f32 v[40:41], v[40:41], v[182:183] op_sel_hi:[1,0]
	v_pk_mul_f32 v[42:43], v[42:43], v[182:183] op_sel_hi:[1,0]
	v_pk_mul_f32 v[76:77], v[76:77], v[182:183] op_sel_hi:[1,0]
	v_pk_mul_f32 v[78:79], v[78:79], v[182:183] op_sel_hi:[1,0]
	v_pk_mul_f32 v[104:105], v[104:105], v[182:183] op_sel_hi:[1,0]
	v_pk_mul_f32 v[106:107], v[106:107], v[182:183] op_sel_hi:[1,0]
	v_pk_mul_f32 v[92:93], v[92:93], v[182:183] op_sel_hi:[1,0]
	v_pk_mul_f32 v[94:95], v[94:95], v[182:183] op_sel_hi:[1,0]
	ds_write_b128 v198, v[40:43]
	ds_write_b128 v198, v[76:79] offset:64
	ds_write_b128 v198, v[104:107] offset:128
	ds_write_b128 v198, v[92:95] offset:192
	s_waitcnt lgkmcnt(4)
	s_waitcnt vmcnt(16)
	v_pk_fma_f32 v[160:161], v[200:201], v[192:193], v[160:161]
	v_pk_fma_f32 v[162:163], v[202:203], v[194:195], v[162:163]
	v_pk_fma_f32 v[164:165], v[204:205], v[192:193], v[164:165]
	v_pk_fma_f32 v[166:167], v[206:207], v[194:195], v[166:167]
	v_pk_fma_f32 v[168:169], v[208:209], v[192:193], v[168:169]
	v_pk_fma_f32 v[170:171], v[210:211], v[194:195], v[170:171]
	v_pk_fma_f32 v[172:173], v[212:213], v[192:193], v[172:173]
	v_pk_fma_f32 v[174:175], v[214:215], v[194:195], v[174:175]
	s_add_u32 s38, s48, 0x80000
	s_addc_u32 s39, s49, 0
	v_fma_f32 v224, v160, v160, v224
	v_fma_f32 v224, v161, v161, v224
	v_fma_f32 v224, v162, v162, v224
	v_fma_f32 v224, v163, v163, v224
	global_store_dwordx4 v232, v[160:163], s[38:39]
	v_fma_f32 v225, v164, v164, v225
	v_fma_f32 v225, v165, v165, v225
	v_fma_f32 v225, v166, v166, v225
	v_fma_f32 v225, v167, v167, v225
	global_store_dwordx4 v233, v[164:167], s[38:39]
	v_fma_f32 v226, v168, v168, v226
	v_fma_f32 v226, v169, v169, v226
	v_fma_f32 v226, v170, v170, v226
	v_fma_f32 v226, v171, v171, v226
	global_store_dwordx4 v234, v[168:171], s[38:39]
	v_fma_f32 v227, v172, v172, v227
	v_fma_f32 v227, v173, v173, v227
	v_fma_f32 v227, v174, v174, v227
	v_fma_f32 v227, v175, v175, v227
	global_store_dwordx4 v235, v[172:175], s[38:39]
	s_cmp_eq_u32 s86, 3
	s_cbranch_scc1 .Loe_nxg2
	s_add_u32 s40, s50, 0x40000
	s_addc_u32 s41, s51, 0
	v_pk_mul_f32 v[200:201], v[160:161], v[184:185]
	v_pk_mul_f32 v[202:203], v[162:163], v[186:187]
	v_pk_mul_f32 v[204:205], v[164:165], v[184:185]
	v_pk_mul_f32 v[206:207], v[166:167], v[186:187]
	v_pk_mul_f32 v[208:209], v[168:169], v[184:185]
	v_pk_mul_f32 v[210:211], v[170:171], v[186:187]
	v_pk_mul_f32 v[212:213], v[172:173], v[184:185]
	v_pk_mul_f32 v[214:215], v[174:175], v[186:187]
	v_cvt_pk_bf16_f32 v200, v200, v201
	v_cvt_pk_bf16_f32 v201, v202, v203
	v_cvt_pk_bf16_f32 v204, v204, v205
	v_cvt_pk_bf16_f32 v205, v206, v207
	v_cvt_pk_bf16_f32 v208, v208, v209
	v_cvt_pk_bf16_f32 v209, v210, v211
	v_cvt_pk_bf16_f32 v212, v212, v213
	v_cvt_pk_bf16_f32 v213, v214, v215
	global_store_dwordx2 v236, v[200:201], s[40:41]
	global_store_dwordx2 v237, v[204:205], s[40:41]
	global_store_dwordx2 v238, v[208:209], s[40:41]
	global_store_dwordx2 v239, v[212:213], s[40:41]
.Loe_nxg2:
	s_nop 1
	s_add_u32 s36, s44, 0x10200
	s_addc_u32 s37, s45, 0
	global_load_dwordx4 v[160:163], v232, s[36:37]
	global_load_dwordx4 v[164:167], v233, s[36:37]
	global_load_dwordx4 v[168:171], v234, s[36:37]
	global_load_dwordx4 v[172:175], v235, s[36:37]
	ds_read_b128 v[200:203], v242
	ds_read_b128 v[204:207], v242 offset:1088
	ds_read_b128 v[208:211], v242 offset:2176
	ds_read_b128 v[212:215], v242 offset:3264
	v_pk_mul_f32 v[80:81], v[80:81], v[176:177] op_sel_hi:[1,0]
	v_pk_mul_f32 v[82:83], v[82:83], v[176:177] op_sel_hi:[1,0]
	v_pk_mul_f32 v[56:57], v[56:57], v[176:177] op_sel_hi:[1,0]
	v_pk_mul_f32 v[58:59], v[58:59], v[176:177] op_sel_hi:[1,0]
	v_pk_mul_f32 v[28:29], v[28:29], v[176:177] op_sel_hi:[1,0]
	v_pk_mul_f32 v[30:31], v[30:31], v[176:177] op_sel_hi:[1,0]
	v_pk_mul_f32 v[12:13], v[12:13], v[176:177] op_sel_hi:[1,0]
	v_pk_mul_f32 v[14:15], v[14:15], v[176:177] op_sel_hi:[1,0]
	ds_write_b128 v198, v[80:83]
	ds_write_b128 v198, v[56:59] offset:64
	ds_write_b128 v198, v[28:31] offset:128
	ds_write_b128 v198, v[12:15] offset:192
	s_waitcnt lgkmcnt(4)
	s_waitcnt vmcnt(16)
	v_pk_fma_f32 v[128:129], v[200:201], v[192:193], v[128:129]
	v_pk_fma_f32 v[130:131], v[202:203], v[194:195], v[130:131]
	v_pk_fma_f32 v[132:133], v[204:205], v[192:193], v[132:133]
	v_pk_fma_f32 v[134:135], v[206:207], v[194:195], v[134:135]
	v_pk_fma_f32 v[136:137], v[208:209], v[192:193], v[136:137]
	v_pk_fma_f32 v[138:139], v[210:211], v[194:195], v[138:139]
	v_pk_fma_f32 v[140:141], v[212:213], v[192:193], v[140:141]
	v_pk_fma_f32 v[142:143], v[214:215], v[194:195], v[142:143]
	s_add_u32 s38, s48, 0x90000
	s_addc_u32 s39, s49, 0
	v_fma_f32 v228, v128, v128, v228
	v_fma_f32 v228, v129, v129, v228
	v_fma_f32 v228, v130, v130, v228
	v_fma_f32 v228, v131, v131, v228
	global_store_dwordx4 v232, v[128:131], s[38:39]
	v_fma_f32 v229, v132, v132, v229
	v_fma_f32 v229, v133, v133, v229
	v_fma_f32 v229, v134, v134, v229
	v_fma_f32 v229, v135, v135, v229
	global_store_dwordx4 v233, v[132:135], s[38:39]
	v_fma_f32 v230, v136, v136, v230
	v_fma_f32 v230, v137, v137, v230
	v_fma_f32 v230, v138, v138, v230
	v_fma_f32 v230, v139, v139, v230
	global_store_dwordx4 v234, v[136:139], s[38:39]
	v_fma_f32 v231, v140, v140, v231
	v_fma_f32 v231, v141, v141, v231
	v_fma_f32 v231, v142, v142, v231
	v_fma_f32 v231, v143, v143, v231
	global_store_dwordx4 v235, v[140:143], s[38:39]
	s_cmp_eq_u32 s86, 3
	s_cbranch_scc1 .Loe_nxg3
	s_add_u32 s40, s50, 0x48000
	s_addc_u32 s41, s51, 0
	v_pk_mul_f32 v[200:201], v[128:129], v[184:185]
	v_pk_mul_f32 v[202:203], v[130:131], v[186:187]
	v_pk_mul_f32 v[204:205], v[132:133], v[184:185]
	v_pk_mul_f32 v[206:207], v[134:135], v[186:187]
	v_pk_mul_f32 v[208:209], v[136:137], v[184:185]
	v_pk_mul_f32 v[210:211], v[138:139], v[186:187]
	v_pk_mul_f32 v[212:213], v[140:141], v[184:185]
	v_pk_mul_f32 v[214:215], v[142:143], v[186:187]
	v_cvt_pk_bf16_f32 v200, v200, v201
	v_cvt_pk_bf16_f32 v201, v202, v203
	v_cvt_pk_bf16_f32 v204, v204, v205
	v_cvt_pk_bf16_f32 v205, v206, v207
	v_cvt_pk_bf16_f32 v208, v208, v209
	v_cvt_pk_bf16_f32 v209, v210, v211
	v_cvt_pk_bf16_f32 v212, v212, v213
	v_cvt_pk_bf16_f32 v213, v214, v215
	global_store_dwordx2 v236, v[200:201], s[40:41]
	global_store_dwordx2 v237, v[204:205], s[40:41]
	global_store_dwordx2 v238, v[208:209], s[40:41]
	global_store_dwordx2 v239, v[212:213], s[40:41]
.Loe_nxg3:
	s_nop 1
	s_add_u32 s36, s44, 0x80200
	s_addc_u32 s37, s45, 0
	global_load_dwordx4 v[128:131], v232, s[36:37]
	global_load_dwordx4 v[132:135], v233, s[36:37]
	global_load_dwordx4 v[136:139], v234, s[36:37]
	global_load_dwordx4 v[140:143], v235, s[36:37]
	ds_read_b128 v[184:187], v243 offset:1024
	ds_read_b128 v[188:191], v243 offset:1040
	s_waitcnt lgkmcnt(0)
	v_mov_b32_e32 v192, v184
	v_mov_b32_e32 v193, v186
	v_mov_b32_e32 v194, v188
	v_mov_b32_e32 v195, v190
	v_mov_b32_e32 v184, v185
	v_mov_b32_e32 v185, v187
	v_mov_b32_e32 v186, v189
	v_mov_b32_e32 v187, v191
	ds_read_b128 v[200:203], v242
	ds_read_b128 v[204:207], v242 offset:1088
	ds_read_b128 v[208:211], v242 offset:2176
	ds_read_b128 v[212:215], v242 offset:3264
	v_pk_mul_f32 v[72:73], v[72:73], v[178:179] op_sel_hi:[1,0]
	v_pk_mul_f32 v[74:75], v[74:75], v[178:179] op_sel_hi:[1,0]
	v_pk_mul_f32 v[44:45], v[44:45], v[178:179] op_sel_hi:[1,0]
	v_pk_mul_f32 v[46:47], v[46:47], v[178:179] op_sel_hi:[1,0]
	v_pk_mul_f32 v[24:25], v[24:25], v[178:179] op_sel_hi:[1,0]
	v_pk_mul_f32 v[26:27], v[26:27], v[178:179] op_sel_hi:[1,0]
	v_pk_mul_f32 v[8:9], v[8:9], v[178:179] op_sel_hi:[1,0]
	v_pk_mul_f32 v[10:11], v[10:11], v[178:179] op_sel_hi:[1,0]
	ds_write_b128 v198, v[72:75]
	ds_write_b128 v198, v[44:47] offset:64
	ds_write_b128 v198, v[24:27] offset:128
	ds_write_b128 v198, v[8:11] offset:192
	s_waitcnt lgkmcnt(4)
	s_waitcnt vmcnt(16)
	v_pk_fma_f32 v[144:145], v[200:201], v[192:193], v[144:145]
	v_pk_fma_f32 v[146:147], v[202:203], v[194:195], v[146:147]
	v_pk_fma_f32 v[148:149], v[204:205], v[192:193], v[148:149]
	v_pk_fma_f32 v[150:151], v[206:207], v[194:195], v[150:151]
	v_pk_fma_f32 v[152:153], v[208:209], v[192:193], v[152:153]
	v_pk_fma_f32 v[154:155], v[210:211], v[194:195], v[154:155]
	v_pk_fma_f32 v[156:157], v[212:213], v[192:193], v[156:157]
	v_pk_fma_f32 v[158:159], v[214:215], v[194:195], v[158:159]
	s_add_u32 s38, s48, 0x200
	s_addc_u32 s39, s49, 0
	v_fma_f32 v216, v144, v144, v216
	v_fma_f32 v216, v145, v145, v216
	v_fma_f32 v216, v146, v146, v216
	v_fma_f32 v216, v147, v147, v216
	global_store_dwordx4 v232, v[144:147], s[38:39]
	v_fma_f32 v217, v148, v148, v217
	v_fma_f32 v217, v149, v149, v217
	v_fma_f32 v217, v150, v150, v217
	v_fma_f32 v217, v151, v151, v217
	global_store_dwordx4 v233, v[148:151], s[38:39]
	v_fma_f32 v218, v152, v152, v218
	v_fma_f32 v218, v153, v153, v218
	v_fma_f32 v218, v154, v154, v218
	v_fma_f32 v218, v155, v155, v218
	global_store_dwordx4 v234, v[152:155], s[38:39]
	v_fma_f32 v219, v156, v156, v219
	v_fma_f32 v219, v157, v157, v219
	v_fma_f32 v219, v158, v158, v219
	v_fma_f32 v219, v159, v159, v219
	global_store_dwordx4 v235, v[156:159], s[38:39]
	s_cmp_eq_u32 s86, 3
	s_cbranch_scc1 .Loe_nxg4
	s_add_u32 s40, s50, 0x100
	s_addc_u32 s41, s51, 0
	v_pk_mul_f32 v[200:201], v[144:145], v[184:185]
	v_pk_mul_f32 v[202:203], v[146:147], v[186:187]
	v_pk_mul_f32 v[204:205], v[148:149], v[184:185]
	v_pk_mul_f32 v[206:207], v[150:151], v[186:187]
	v_pk_mul_f32 v[208:209], v[152:153], v[184:185]
	v_pk_mul_f32 v[210:211], v[154:155], v[186:187]
	v_pk_mul_f32 v[212:213], v[156:157], v[184:185]
	v_pk_mul_f32 v[214:215], v[158:159], v[186:187]
	v_cvt_pk_bf16_f32 v200, v200, v201
	v_cvt_pk_bf16_f32 v201, v202, v203
	v_cvt_pk_bf16_f32 v204, v204, v205
	v_cvt_pk_bf16_f32 v205, v206, v207
	v_cvt_pk_bf16_f32 v208, v208, v209
	v_cvt_pk_bf16_f32 v209, v210, v211
	v_cvt_pk_bf16_f32 v212, v212, v213
	v_cvt_pk_bf16_f32 v213, v214, v215
	global_store_dwordx2 v236, v[200:201], s[40:41]
	global_store_dwordx2 v237, v[204:205], s[40:41]
	global_store_dwordx2 v238, v[208:209], s[40:41]
	global_store_dwordx2 v239, v[212:213], s[40:41]
.Loe_nxg4:
	s_nop 1
	s_add_u32 s36, s44, 0x90200
	s_addc_u32 s37, s45, 0
	global_load_dwordx4 v[144:147], v232, s[36:37]
	global_load_dwordx4 v[148:151], v233, s[36:37]
	global_load_dwordx4 v[152:155], v234, s[36:37]
	global_load_dwordx4 v[156:159], v235, s[36:37]
	ds_read_b128 v[200:203], v242
	ds_read_b128 v[204:207], v242 offset:1088
	ds_read_b128 v[208:211], v242 offset:2176
	ds_read_b128 v[212:215], v242 offset:3264
	v_pk_mul_f32 v[68:69], v[68:69], v[180:181] op_sel_hi:[1,0]
	v_pk_mul_f32 v[70:71], v[70:71], v[180:181] op_sel_hi:[1,0]
	v_pk_mul_f32 v[36:37], v[36:37], v[180:181] op_sel_hi:[1,0]
	v_pk_mul_f32 v[38:39], v[38:39], v[180:181] op_sel_hi:[1,0]
	v_pk_mul_f32 v[20:21], v[20:21], v[180:181] op_sel_hi:[1,0]
	v_pk_mul_f32 v[22:23], v[22:23], v[180:181] op_sel_hi:[1,0]
	v_pk_mul_f32 v[4:5], v[4:5], v[180:181] op_sel_hi:[1,0]
	v_pk_mul_f32 v[6:7], v[6:7], v[180:181] op_sel_hi:[1,0]
	ds_write_b128 v198, v[68:71]
	ds_write_b128 v198, v[36:39] offset:64
	ds_write_b128 v198, v[20:23] offset:128
	ds_write_b128 v198, v[4:7] offset:192
	s_waitcnt lgkmcnt(4)
	s_waitcnt vmcnt(16)
	v_pk_fma_f32 v[160:161], v[200:201], v[192:193], v[160:161]
	v_pk_fma_f32 v[162:163], v[202:203], v[194:195], v[162:163]
	v_pk_fma_f32 v[164:165], v[204:205], v[192:193], v[164:165]
	v_pk_fma_f32 v[166:167], v[206:207], v[194:195], v[166:167]
	v_pk_fma_f32 v[168:169], v[208:209], v[192:193], v[168:169]
	v_pk_fma_f32 v[170:171], v[210:211], v[194:195], v[170:171]
	v_pk_fma_f32 v[172:173], v[212:213], v[192:193], v[172:173]
	v_pk_fma_f32 v[174:175], v[214:215], v[194:195], v[174:175]
	s_add_u32 s38, s48, 0x10200
	s_addc_u32 s39, s49, 0
	v_fma_f32 v220, v160, v160, v220
	v_fma_f32 v220, v161, v161, v220
	v_fma_f32 v220, v162, v162, v220
	v_fma_f32 v220, v163, v163, v220
	global_store_dwordx4 v232, v[160:163], s[38:39]
	v_fma_f32 v221, v164, v164, v221
	v_fma_f32 v221, v165, v165, v221
	v_fma_f32 v221, v166, v166, v221
	v_fma_f32 v221, v167, v167, v221
	global_store_dwordx4 v233, v[164:167], s[38:39]
	v_fma_f32 v222, v168, v168, v222
	v_fma_f32 v222, v169, v169, v222
	v_fma_f32 v222, v170, v170, v222
	v_fma_f32 v222, v171, v171, v222
	global_store_dwordx4 v234, v[168:171], s[38:39]
	v_fma_f32 v223, v172, v172, v223
	v_fma_f32 v223, v173, v173, v223
	v_fma_f32 v223, v174, v174, v223
	v_fma_f32 v223, v175, v175, v223
	global_store_dwordx4 v235, v[172:175], s[38:39]
	s_cmp_eq_u32 s86, 3
	s_cbranch_scc1 .Loe_nxg5
	s_add_u32 s40, s50, 0x8100
	s_addc_u32 s41, s51, 0
	v_pk_mul_f32 v[200:201], v[160:161], v[184:185]
	v_pk_mul_f32 v[202:203], v[162:163], v[186:187]
	v_pk_mul_f32 v[204:205], v[164:165], v[184:185]
	v_pk_mul_f32 v[206:207], v[166:167], v[186:187]
	v_pk_mul_f32 v[208:209], v[168:169], v[184:185]
	v_pk_mul_f32 v[210:211], v[170:171], v[186:187]
	v_pk_mul_f32 v[212:213], v[172:173], v[184:185]
	v_pk_mul_f32 v[214:215], v[174:175], v[186:187]
	v_cvt_pk_bf16_f32 v200, v200, v201
	v_cvt_pk_bf16_f32 v201, v202, v203
	v_cvt_pk_bf16_f32 v204, v204, v205
	v_cvt_pk_bf16_f32 v205, v206, v207
	v_cvt_pk_bf16_f32 v208, v208, v209
	v_cvt_pk_bf16_f32 v209, v210, v211
	v_cvt_pk_bf16_f32 v212, v212, v213
	v_cvt_pk_bf16_f32 v213, v214, v215
	global_store_dwordx2 v236, v[200:201], s[40:41]
	global_store_dwordx2 v237, v[204:205], s[40:41]
	global_store_dwordx2 v238, v[208:209], s[40:41]
	global_store_dwordx2 v239, v[212:213], s[40:41]
.Loe_nxg5:
	ds_read_b128 v[200:203], v242
	ds_read_b128 v[204:207], v242 offset:1088
	ds_read_b128 v[208:211], v242 offset:2176
	ds_read_b128 v[212:215], v242 offset:3264
	v_pk_mul_f32 v[64:65], v[64:65], v[182:183] op_sel_hi:[1,0]
	v_pk_mul_f32 v[66:67], v[66:67], v[182:183] op_sel_hi:[1,0]
	v_pk_mul_f32 v[32:33], v[32:33], v[182:183] op_sel_hi:[1,0]
	v_pk_mul_f32 v[34:35], v[34:35], v[182:183] op_sel_hi:[1,0]
	v_pk_mul_f32 v[16:17], v[16:17], v[182:183] op_sel_hi:[1,0]
	v_pk_mul_f32 v[18:19], v[18:19], v[182:183] op_sel_hi:[1,0]
	v_pk_mul_f32 v[0:1], v[0:1], v[182:183] op_sel_hi:[1,0]
	v_pk_mul_f32 v[2:3], v[2:3], v[182:183] op_sel_hi:[1,0]
	ds_write_b128 v198, v[64:67]
	ds_write_b128 v198, v[32:35] offset:64
	ds_write_b128 v198, v[16:19] offset:128
	ds_write_b128 v198, v[0:3] offset:192
	s_waitcnt lgkmcnt(4)
	s_waitcnt vmcnt(12)
	v_pk_fma_f32 v[128:129], v[200:201], v[192:193], v[128:129]
	v_pk_fma_f32 v[130:131], v[202:203], v[194:195], v[130:131]
	v_pk_fma_f32 v[132:133], v[204:205], v[192:193], v[132:133]
	v_pk_fma_f32 v[134:135], v[206:207], v[194:195], v[134:135]
	v_pk_fma_f32 v[136:137], v[208:209], v[192:193], v[136:137]
	v_pk_fma_f32 v[138:139], v[210:211], v[194:195], v[138:139]
	v_pk_fma_f32 v[140:141], v[212:213], v[192:193], v[140:141]
	v_pk_fma_f32 v[142:143], v[214:215], v[194:195], v[142:143]
	s_add_u32 s38, s48, 0x80200
	s_addc_u32 s39, s49, 0
	v_fma_f32 v224, v128, v128, v224
	v_fma_f32 v224, v129, v129, v224
	v_fma_f32 v224, v130, v130, v224
	v_fma_f32 v224, v131, v131, v224
	global_store_dwordx4 v232, v[128:131], s[38:39]
	v_fma_f32 v225, v132, v132, v225
	v_fma_f32 v225, v133, v133, v225
	v_fma_f32 v225, v134, v134, v225
	v_fma_f32 v225, v135, v135, v225
	global_store_dwordx4 v233, v[132:135], s[38:39]
	v_fma_f32 v226, v136, v136, v226
	v_fma_f32 v226, v137, v137, v226
	v_fma_f32 v226, v138, v138, v226
	v_fma_f32 v226, v139, v139, v226
	global_store_dwordx4 v234, v[136:139], s[38:39]
	v_fma_f32 v227, v140, v140, v227
	v_fma_f32 v227, v141, v141, v227
	v_fma_f32 v227, v142, v142, v227
	v_fma_f32 v227, v143, v143, v227
	global_store_dwordx4 v235, v[140:143], s[38:39]
	s_cmp_eq_u32 s86, 3
	s_cbranch_scc1 .Loe_nxg6
	s_add_u32 s40, s50, 0x40100
	s_addc_u32 s41, s51, 0
	v_pk_mul_f32 v[200:201], v[128:129], v[184:185]
	v_pk_mul_f32 v[202:203], v[130:131], v[186:187]
	v_pk_mul_f32 v[204:205], v[132:133], v[184:185]
	v_pk_mul_f32 v[206:207], v[134:135], v[186:187]
	v_pk_mul_f32 v[208:209], v[136:137], v[184:185]
	v_pk_mul_f32 v[210:211], v[138:139], v[186:187]
	v_pk_mul_f32 v[212:213], v[140:141], v[184:185]
	v_pk_mul_f32 v[214:215], v[142:143], v[186:187]
	v_cvt_pk_bf16_f32 v200, v200, v201
	v_cvt_pk_bf16_f32 v201, v202, v203
	v_cvt_pk_bf16_f32 v204, v204, v205
	v_cvt_pk_bf16_f32 v205, v206, v207
	v_cvt_pk_bf16_f32 v208, v208, v209
	v_cvt_pk_bf16_f32 v209, v210, v211
	v_cvt_pk_bf16_f32 v212, v212, v213
	v_cvt_pk_bf16_f32 v213, v214, v215
	global_store_dwordx2 v236, v[200:201], s[40:41]
	global_store_dwordx2 v237, v[204:205], s[40:41]
	global_store_dwordx2 v238, v[208:209], s[40:41]
	global_store_dwordx2 v239, v[212:213], s[40:41]
.Loe_nxg6:
	ds_read_b128 v[200:203], v242
	ds_read_b128 v[204:207], v242 offset:1088
	ds_read_b128 v[208:211], v242 offset:2176
	ds_read_b128 v[212:215], v242 offset:3264
	s_waitcnt lgkmcnt(0)
	s_waitcnt vmcnt(8)
	v_pk_fma_f32 v[144:145], v[200:201], v[192:193], v[144:145]
	v_pk_fma_f32 v[146:147], v[202:203], v[194:195], v[146:147]
	v_pk_fma_f32 v[148:149], v[204:205], v[192:193], v[148:149]
	v_pk_fma_f32 v[150:151], v[206:207], v[194:195], v[150:151]
	v_pk_fma_f32 v[152:153], v[208:209], v[192:193], v[152:153]
	v_pk_fma_f32 v[154:155], v[210:211], v[194:195], v[154:155]
	v_pk_fma_f32 v[156:157], v[212:213], v[192:193], v[156:157]
	v_pk_fma_f32 v[158:159], v[214:215], v[194:195], v[158:159]
	s_add_u32 s38, s48, 0x90200
	s_addc_u32 s39, s49, 0
	v_fma_f32 v228, v144, v144, v228
	v_fma_f32 v228, v145, v145, v228
	v_fma_f32 v228, v146, v146, v228
	v_fma_f32 v228, v147, v147, v228
	global_store_dwordx4 v232, v[144:147], s[38:39]
	v_fma_f32 v229, v148, v148, v229
	v_fma_f32 v229, v149, v149, v229
	v_fma_f32 v229, v150, v150, v229
	v_fma_f32 v229, v151, v151, v229
	global_store_dwordx4 v233, v[148:151], s[38:39]
	v_fma_f32 v230, v152, v152, v230
	v_fma_f32 v230, v153, v153, v230
	v_fma_f32 v230, v154, v154, v230
	v_fma_f32 v230, v155, v155, v230
	global_store_dwordx4 v234, v[152:155], s[38:39]
	v_fma_f32 v231, v156, v156, v231
	v_fma_f32 v231, v157, v157, v231
	v_fma_f32 v231, v158, v158, v231
	v_fma_f32 v231, v159, v159, v231
	global_store_dwordx4 v235, v[156:159], s[38:39]
	s_cmp_eq_u32 s86, 3
	s_cbranch_scc1 .Loe_nxg7
	s_add_u32 s40, s50, 0x48100
	s_addc_u32 s41, s51, 0
	v_pk_mul_f32 v[200:201], v[144:145], v[184:185]
	v_pk_mul_f32 v[202:203], v[146:147], v[186:187]
	v_pk_mul_f32 v[204:205], v[148:149], v[184:185]
	v_pk_mul_f32 v[206:207], v[150:151], v[186:187]
	v_pk_mul_f32 v[208:209], v[152:153], v[184:185]
	v_pk_mul_f32 v[210:211], v[154:155], v[186:187]
	v_pk_mul_f32 v[212:213], v[156:157], v[184:185]
	v_pk_mul_f32 v[214:215], v[158:159], v[186:187]
	v_cvt_pk_bf16_f32 v200, v200, v201
	v_cvt_pk_bf16_f32 v201, v202, v203
	v_cvt_pk_bf16_f32 v204, v204, v205
	v_cvt_pk_bf16_f32 v205, v206, v207
	v_cvt_pk_bf16_f32 v208, v208, v209
	v_cvt_pk_bf16_f32 v209, v210, v211
	v_cvt_pk_bf16_f32 v212, v212, v213
	v_cvt_pk_bf16_f32 v213, v214, v215
	global_store_dwordx2 v236, v[200:201], s[40:41]
	global_store_dwordx2 v237, v[204:205], s[40:41]
	global_store_dwordx2 v238, v[208:209], s[40:41]
	global_store_dwordx2 v239, v[212:213], s[40:41]
.Loe_nxg7:
	v_add_f32_dpp v216, v216, v216 row_ror:8 row_mask:0xf bank_mask:0xf
	v_add_f32_dpp v217, v217, v217 row_ror:8 row_mask:0xf bank_mask:0xf
	v_add_f32_dpp v218, v218, v218 row_ror:8 row_mask:0xf bank_mask:0xf
	v_add_f32_dpp v219, v219, v219 row_ror:8 row_mask:0xf bank_mask:0xf
	v_add_f32_dpp v220, v220, v220 row_ror:8 row_mask:0xf bank_mask:0xf
	v_add_f32_dpp v221, v221, v221 row_ror:8 row_mask:0xf bank_mask:0xf
	v_add_f32_dpp v222, v222, v222 row_ror:8 row_mask:0xf bank_mask:0xf
	v_add_f32_dpp v223, v223, v223 row_ror:8 row_mask:0xf bank_mask:0xf
	v_add_f32_dpp v224, v224, v224 row_ror:8 row_mask:0xf bank_mask:0xf
	v_add_f32_dpp v225, v225, v225 row_ror:8 row_mask:0xf bank_mask:0xf
	v_add_f32_dpp v226, v226, v226 row_ror:8 row_mask:0xf bank_mask:0xf
	v_add_f32_dpp v227, v227, v227 row_ror:8 row_mask:0xf bank_mask:0xf
	v_add_f32_dpp v228, v228, v228 row_ror:8 row_mask:0xf bank_mask:0xf
	v_add_f32_dpp v229, v229, v229 row_ror:8 row_mask:0xf bank_mask:0xf
	v_add_f32_dpp v230, v230, v230 row_ror:8 row_mask:0xf bank_mask:0xf
	v_add_f32_dpp v231, v231, v231 row_ror:8 row_mask:0xf bank_mask:0xf
	v_add_f32_dpp v216, v216, v216 row_ror:4 row_mask:0xf bank_mask:0xf
	v_add_f32_dpp v217, v217, v217 row_ror:4 row_mask:0xf bank_mask:0xf
	v_add_f32_dpp v218, v218, v218 row_ror:4 row_mask:0xf bank_mask:0xf
	v_add_f32_dpp v219, v219, v219 row_ror:4 row_mask:0xf bank_mask:0xf
	v_add_f32_dpp v220, v220, v220 row_ror:4 row_mask:0xf bank_mask:0xf
	v_add_f32_dpp v221, v221, v221 row_ror:4 row_mask:0xf bank_mask:0xf
	v_add_f32_dpp v222, v222, v222 row_ror:4 row_mask:0xf bank_mask:0xf
	v_add_f32_dpp v223, v223, v223 row_ror:4 row_mask:0xf bank_mask:0xf
	v_add_f32_dpp v224, v224, v224 row_ror:4 row_mask:0xf bank_mask:0xf
	v_add_f32_dpp v225, v225, v225 row_ror:4 row_mask:0xf bank_mask:0xf
	v_add_f32_dpp v226, v226, v226 row_ror:4 row_mask:0xf bank_mask:0xf
	v_add_f32_dpp v227, v227, v227 row_ror:4 row_mask:0xf bank_mask:0xf
	v_add_f32_dpp v228, v228, v228 row_ror:4 row_mask:0xf bank_mask:0xf
	v_add_f32_dpp v229, v229, v229 row_ror:4 row_mask:0xf bank_mask:0xf
	v_add_f32_dpp v230, v230, v230 row_ror:4 row_mask:0xf bank_mask:0xf
	v_add_f32_dpp v231, v231, v231 row_ror:4 row_mask:0xf bank_mask:0xf
	v_add_f32_dpp v216, v216, v216 row_ror:2 row_mask:0xf bank_mask:0xf
	v_add_f32_dpp v217, v217, v217 row_ror:2 row_mask:0xf bank_mask:0xf
	v_add_f32_dpp v218, v218, v218 row_ror:2 row_mask:0xf bank_mask:0xf
	v_add_f32_dpp v219, v219, v219 row_ror:2 row_mask:0xf bank_mask:0xf
	v_add_f32_dpp v220, v220, v220 row_ror:2 row_mask:0xf bank_mask:0xf
	v_add_f32_dpp v221, v221, v221 row_ror:2 row_mask:0xf bank_mask:0xf
	v_add_f32_dpp v222, v222, v222 row_ror:2 row_mask:0xf bank_mask:0xf
	v_add_f32_dpp v223, v223, v223 row_ror:2 row_mask:0xf bank_mask:0xf
	v_add_f32_dpp v224, v224, v224 row_ror:2 row_mask:0xf bank_mask:0xf
	v_add_f32_dpp v225, v225, v225 row_ror:2 row_mask:0xf bank_mask:0xf
	v_add_f32_dpp v226, v226, v226 row_ror:2 row_mask:0xf bank_mask:0xf
	v_add_f32_dpp v227, v227, v227 row_ror:2 row_mask:0xf bank_mask:0xf
	v_add_f32_dpp v228, v228, v228 row_ror:2 row_mask:0xf bank_mask:0xf
	v_add_f32_dpp v229, v229, v229 row_ror:2 row_mask:0xf bank_mask:0xf
	v_add_f32_dpp v230, v230, v230 row_ror:2 row_mask:0xf bank_mask:0xf
	v_add_f32_dpp v231, v231, v231 row_ror:2 row_mask:0xf bank_mask:0xf
	v_add_f32_dpp v216, v216, v216 row_ror:1 row_mask:0xf bank_mask:0xf
	v_add_f32_dpp v217, v217, v217 row_ror:1 row_mask:0xf bank_mask:0xf
	v_add_f32_dpp v218, v218, v218 row_ror:1 row_mask:0xf bank_mask:0xf
	v_add_f32_dpp v219, v219, v219 row_ror:1 row_mask:0xf bank_mask:0xf
	v_add_f32_dpp v220, v220, v220 row_ror:1 row_mask:0xf bank_mask:0xf
	v_add_f32_dpp v221, v221, v221 row_ror:1 row_mask:0xf bank_mask:0xf
	v_add_f32_dpp v222, v222, v222 row_ror:1 row_mask:0xf bank_mask:0xf
	v_add_f32_dpp v223, v223, v223 row_ror:1 row_mask:0xf bank_mask:0xf
	v_add_f32_dpp v224, v224, v224 row_ror:1 row_mask:0xf bank_mask:0xf
	v_add_f32_dpp v225, v225, v225 row_ror:1 row_mask:0xf bank_mask:0xf
	v_add_f32_dpp v226, v226, v226 row_ror:1 row_mask:0xf bank_mask:0xf
	v_add_f32_dpp v227, v227, v227 row_ror:1 row_mask:0xf bank_mask:0xf
	v_add_f32_dpp v228, v228, v228 row_ror:1 row_mask:0xf bank_mask:0xf
	v_add_f32_dpp v229, v229, v229 row_ror:1 row_mask:0xf bank_mask:0xf
	v_add_f32_dpp v230, v230, v230 row_ror:1 row_mask:0xf bank_mask:0xf
	v_add_f32_dpp v231, v231, v231 row_ror:1 row_mask:0xf bank_mask:0xf
	s_add_u32 s46, s42, 0x1000
	s_addc_u32 s47, s43, 0
	s_mov_b32 exec_lo, 0x10001
	s_mov_b32 exec_hi, 0x10001
	global_store_dword v244, v216, s[42:43]
	global_store_dword v244, v217, s[42:43] offset:128
	global_store_dword v244, v218, s[42:43] offset:256
	global_store_dword v244, v219, s[42:43] offset:384
	global_store_dword v244, v220, s[42:43] offset:512
	global_store_dword v244, v221, s[42:43] offset:640
	global_store_dword v244, v222, s[42:43] offset:768
	global_store_dword v244, v223, s[42:43] offset:896
	global_store_dword v244, v224, s[46:47]
	global_store_dword v244, v225, s[46:47] offset:128
	global_store_dword v244, v226, s[46:47] offset:256
	global_store_dword v244, v227, s[46:47] offset:384
	global_store_dword v244, v228, s[46:47] offset:512
	global_store_dword v244, v229, s[46:47] offset:640
	global_store_dword v244, v230, s[46:47] offset:768
	global_store_dword v244, v231, s[46:47] offset:896
	s_mov_b64 exec, -1
	s_mov_b64 s[0:1], exec
	s_branch .LBB0_534
